# GEMM loop: 4/4 DMA split, moved pairs issued after the ds_reads in saddr form
# baseline (speedup 1.0000x reference)
.LBB0_176:
	v_add_u32_e32 v130, 0x10000, v243
	v_add_u32_e32 v142, 0x14000, v243
	ds_read_b128 v[146:149], v130
	ds_read_b128 v[150:153], v130 offset:1024
	ds_read_b128 v[154:157], v130 offset:2048
	ds_read_b128 v[158:161], v130 offset:3072
	ds_read_b128 v[130:133], v142
	ds_read_b128 v[134:137], v142 offset:1024
	ds_read_b128 v[138:141], v142 offset:2048
	ds_read_b128 v[142:145], v142 offset:3072
	v_lshl_add_u64 v[246:247], v[234:235], 0, s[80:81]
	s_add_i32 m0, s8, 0xc000
	s_waitcnt lgkmcnt(0)
	ds_read_b128 v[174:177], v244
	ds_read_b128 v[190:193], v244 offset:1024
	ds_read_b128 v[170:173], v244 offset:2048
	ds_read_b128 v[186:189], v244 offset:3072
	ds_read_b128 v[166:169], v244 offset:4096
	ds_read_b128 v[182:185], v244 offset:5120
	ds_read_b128 v[162:165], v244 offset:6144
	ds_read_b128 v[178:181], v244 offset:7168
	s_mov_b32 m0, s55
	s_nop 0
	global_load_lds_dwordx4 v194, s[100:101]
	s_mov_b32 m0, s67
	s_nop 0
	global_load_lds_dwordx4 v196, s[100:101]
	s_add_i32 m0, s8, 0xc000
	s_nop 0
	global_load_lds_dwordx4 v[246:247], off
	v_lshl_add_u64 v[246:247], v[236:237], 0, s[80:81]
	s_add_i32 m0, s8, 0xe000
	s_nop 0
	global_load_lds_dwordx4 v[246:247], off
	s_waitcnt vmcnt(8)
	s_waitcnt lgkmcnt(0)
	s_barrier
	s_setprio 1
	s_waitcnt lgkmcnt(0)
	v_mfma_f32_16x16x32_bf16 v[118:121], v[146:149], v[174:177], v[118:121]
	v_mfma_f32_16x16x32_bf16 v[126:129], v[154:157], v[174:177], v[126:129]
	v_mfma_f32_16x16x32_bf16 v[102:105], v[146:149], v[170:173], v[102:105]
	v_mfma_f32_16x16x32_bf16 v[110:113], v[154:157], v[170:173], v[110:113]
	v_mfma_f32_16x16x32_bf16 v[86:89], v[146:149], v[166:169], v[86:89]
	v_mfma_f32_16x16x32_bf16 v[94:97], v[154:157], v[166:169], v[94:97]
	v_mfma_f32_16x16x32_bf16 v[70:73], v[146:149], v[162:165], v[70:73]
	v_mfma_f32_16x16x32_bf16 v[78:81], v[154:157], v[162:165], v[78:81]
	v_mfma_f32_16x16x32_bf16 v[118:121], v[150:153], v[190:193], v[118:121]
	v_mfma_f32_16x16x32_bf16 v[126:129], v[158:161], v[190:193], v[126:129]
	v_mfma_f32_16x16x32_bf16 v[102:105], v[150:153], v[186:189], v[102:105]
	v_mfma_f32_16x16x32_bf16 v[110:113], v[158:161], v[186:189], v[110:113]
	v_mfma_f32_16x16x32_bf16 v[86:89], v[150:153], v[182:185], v[86:89]
	v_mfma_f32_16x16x32_bf16 v[94:97], v[158:161], v[182:185], v[94:97]
	v_mfma_f32_16x16x32_bf16 v[70:73], v[150:153], v[178:181], v[70:73]
	v_mfma_f32_16x16x32_bf16 v[78:81], v[158:161], v[178:181], v[78:81]
	s_setprio 0
	s_setprio 1
	v_mfma_f32_16x16x32_bf16 v[122:125], v[130:133], v[174:177], v[122:125]
	v_mfma_f32_16x16x32_bf16 v[114:117], v[138:141], v[174:177], v[114:117]
	v_mfma_f32_16x16x32_bf16 v[106:109], v[130:133], v[170:173], v[106:109]
	v_mfma_f32_16x16x32_bf16 v[98:101], v[138:141], v[170:173], v[98:101]
	v_mfma_f32_16x16x32_bf16 v[90:93], v[130:133], v[166:169], v[90:93]
	v_mfma_f32_16x16x32_bf16 v[82:85], v[138:141], v[166:169], v[82:85]
	v_mfma_f32_16x16x32_bf16 v[74:77], v[130:133], v[162:165], v[74:77]
	v_mfma_f32_16x16x32_bf16 v[66:69], v[138:141], v[162:165], v[66:69]
	v_mfma_f32_16x16x32_bf16 v[122:125], v[134:137], v[190:193], v[122:125]
	v_mfma_f32_16x16x32_bf16 v[114:117], v[142:145], v[190:193], v[114:117]
	v_mfma_f32_16x16x32_bf16 v[106:109], v[134:137], v[186:189], v[106:109]
	v_mfma_f32_16x16x32_bf16 v[98:101], v[142:145], v[186:189], v[98:101]
	v_mfma_f32_16x16x32_bf16 v[90:93], v[134:137], v[182:185], v[90:93]
	v_mfma_f32_16x16x32_bf16 v[82:85], v[142:145], v[182:185], v[82:85]
	v_mfma_f32_16x16x32_bf16 v[74:77], v[134:137], v[178:181], v[74:77]
	v_mfma_f32_16x16x32_bf16 v[66:69], v[142:145], v[178:181], v[66:69]
	s_setprio 0
	s_barrier
	v_cndmask_b32_e64 v246, 0, 1, s[50:51]
	v_cmp_ne_u32_e64 s[48:49], 1, v246
	s_andn2_b64 vcc, exec, s[50:51]
	s_cbranch_vccnz .LBB0_178
	ds_read_b128 v[174:177], v244 offset:16384
	ds_read_b128 v[190:193], v244 offset:17408
	ds_read_b128 v[170:173], v244 offset:18432
	ds_read_b128 v[186:189], v244 offset:19456
	ds_read_b128 v[166:169], v244 offset:20480
	ds_read_b128 v[182:185], v244 offset:21504
	ds_read_b128 v[162:165], v244 offset:22528
	ds_read_b128 v[178:181], v244 offset:23552

.LBB0_180:
	s_and_b64 vcc, s[46:47], s[86:87]
	v_cndmask_b32_e64 v131, v233, 0, vcc
	v_cndmask_b32_e32 v130, v232, v198, vcc
	v_lshl_add_u64 v[246:247], s[84:85], 0, v[130:131]
	s_barrier
	v_add_u32_e32 v130, 0x18000, v243
	v_add_u32_e32 v142, 0x1c000, v243
	ds_read_b128 v[146:149], v130
	ds_read_b128 v[150:153], v130 offset:1024
	ds_read_b128 v[154:157], v130 offset:2048
	ds_read_b128 v[158:161], v130 offset:3072
	ds_read_b128 v[130:133], v142
	ds_read_b128 v[134:137], v142 offset:1024
	ds_read_b128 v[138:141], v142 offset:2048
	ds_read_b128 v[142:145], v142 offset:3072
	s_mov_b32 m0, s14
	v_lshl_add_u64 v[248:249], v[246:247], 0, v[194:195]
	s_waitcnt lgkmcnt(0)
	ds_read_b128 v[174:177], v244 offset:32768
	ds_read_b128 v[190:193], v244 offset:33792
	ds_read_b128 v[170:173], v244 offset:34816
	ds_read_b128 v[186:189], v244 offset:35840
	ds_read_b128 v[166:169], v244 offset:36864
	ds_read_b128 v[182:185], v244 offset:37888
	ds_read_b128 v[162:165], v244 offset:38912
	ds_read_b128 v[178:181], v244 offset:39936
	s_mov_b32 m0, s8
	s_nop 0
	global_load_lds_dwordx4 v194, s[98:99]
	s_mov_b32 m0, s13
	s_nop 0
	global_load_lds_dwordx4 v196, s[98:99]
	s_mov_b32 m0, s14
	s_nop 0
	global_load_lds_dwordx4 v[248:249], off
	v_lshl_add_u64 v[246:247], v[246:247], 0, v[196:197]
	s_mov_b32 m0, s15
	s_nop 0
	global_load_lds_dwordx4 v[246:247], off
	s_waitcnt vmcnt(8)
	s_waitcnt lgkmcnt(0)
	s_barrier
	s_setprio 1
	s_waitcnt lgkmcnt(0)
	v_mfma_f32_16x16x32_bf16 v[118:121], v[146:149], v[174:177], v[118:121]
	v_mfma_f32_16x16x32_bf16 v[126:129], v[154:157], v[174:177], v[126:129]
	v_mfma_f32_16x16x32_bf16 v[102:105], v[146:149], v[170:173], v[102:105]
	v_mfma_f32_16x16x32_bf16 v[110:113], v[154:157], v[170:173], v[110:113]
	v_mfma_f32_16x16x32_bf16 v[86:89], v[146:149], v[166:169], v[86:89]
	v_mfma_f32_16x16x32_bf16 v[94:97], v[154:157], v[166:169], v[94:97]
	v_mfma_f32_16x16x32_bf16 v[70:73], v[146:149], v[162:165], v[70:73]
	v_mfma_f32_16x16x32_bf16 v[78:81], v[154:157], v[162:165], v[78:81]
	v_mfma_f32_16x16x32_bf16 v[118:121], v[150:153], v[190:193], v[118:121]
	v_mfma_f32_16x16x32_bf16 v[126:129], v[158:161], v[190:193], v[126:129]
	v_mfma_f32_16x16x32_bf16 v[102:105], v[150:153], v[186:189], v[102:105]
	v_mfma_f32_16x16x32_bf16 v[110:113], v[158:161], v[186:189], v[110:113]
	v_mfma_f32_16x16x32_bf16 v[86:89], v[150:153], v[182:185], v[86:89]
	v_mfma_f32_16x16x32_bf16 v[94:97], v[158:161], v[182:185], v[94:97]
	v_mfma_f32_16x16x32_bf16 v[70:73], v[150:153], v[178:181], v[70:73]
	v_mfma_f32_16x16x32_bf16 v[78:81], v[158:161], v[178:181], v[78:81]
	s_setprio 0
	s_setprio 1
	v_mfma_f32_16x16x32_bf16 v[122:125], v[130:133], v[174:177], v[122:125]
	v_mfma_f32_16x16x32_bf16 v[114:117], v[138:141], v[174:177], v[114:117]
	v_mfma_f32_16x16x32_bf16 v[106:109], v[130:133], v[170:173], v[106:109]
	v_mfma_f32_16x16x32_bf16 v[98:101], v[138:141], v[170:173], v[98:101]
	v_mfma_f32_16x16x32_bf16 v[90:93], v[130:133], v[166:169], v[90:93]
	v_mfma_f32_16x16x32_bf16 v[82:85], v[138:141], v[166:169], v[82:85]
	v_mfma_f32_16x16x32_bf16 v[74:77], v[130:133], v[162:165], v[74:77]
	v_mfma_f32_16x16x32_bf16 v[66:69], v[138:141], v[162:165], v[66:69]
	v_mfma_f32_16x16x32_bf16 v[122:125], v[134:137], v[190:193], v[122:125]
	v_mfma_f32_16x16x32_bf16 v[114:117], v[142:145], v[190:193], v[114:117]
	v_mfma_f32_16x16x32_bf16 v[106:109], v[134:137], v[186:189], v[106:109]
	v_mfma_f32_16x16x32_bf16 v[98:101], v[142:145], v[186:189], v[98:101]
	v_mfma_f32_16x16x32_bf16 v[90:93], v[134:137], v[182:185], v[90:93]
	v_mfma_f32_16x16x32_bf16 v[82:85], v[142:145], v[182:185], v[82:85]
	v_mfma_f32_16x16x32_bf16 v[74:77], v[134:137], v[178:181], v[74:77]
	v_mfma_f32_16x16x32_bf16 v[66:69], v[142:145], v[178:181], v[66:69]
	s_setprio 0
	s_barrier
	s_and_b64 vcc, exec, s[48:49]
	s_cbranch_vccnz .LBB0_182
	ds_read_b128 v[174:177], v244 offset:49152
	ds_read_b128 v[190:193], v244 offset:50176
	ds_read_b128 v[170:173], v244 offset:51200
	ds_read_b128 v[186:189], v244 offset:52224
	ds_read_b128 v[166:169], v244 offset:53248
	ds_read_b128 v[182:185], v244 offset:54272
	ds_read_b128 v[162:165], v244 offset:55296
	ds_read_b128 v[178:181], v244 offset:56320

.LBB0_559:
	ds_read_b128 v[146:149], v227
	ds_read_b128 v[150:153], v227 offset:1024
	ds_read_b128 v[154:157], v227 offset:2048
	ds_read_b128 v[158:161], v227 offset:3072
	ds_read_b128 v[130:133], v228
	ds_read_b128 v[134:137], v228 offset:1024
	ds_read_b128 v[138:141], v228 offset:2048
	ds_read_b128 v[142:145], v228 offset:3072
	v_lshl_add_u64 v[234:235], v[216:217], 0, s[58:59]
	s_add_i32 m0, s8, 0xc000
	s_waitcnt lgkmcnt(0)
	ds_read_b128 v[174:177], v229
	ds_read_b128 v[190:193], v229 offset:1024
	ds_read_b128 v[170:173], v229 offset:2048
	ds_read_b128 v[186:189], v229 offset:3072
	ds_read_b128 v[166:169], v229 offset:4096
	ds_read_b128 v[182:185], v229 offset:5120
	ds_read_b128 v[162:165], v229 offset:6144
	ds_read_b128 v[178:181], v229 offset:7168
	s_mov_b32 m0, s55
	s_nop 0
	global_load_lds_dwordx4 v194, s[100:101]
	s_mov_b32 m0, s67
	s_nop 0
	global_load_lds_dwordx4 v196, s[100:101]
	s_add_i32 m0, s8, 0xc000
	s_nop 0
	global_load_lds_dwordx4 v[234:235], off
	v_lshl_add_u64 v[234:235], v[218:219], 0, s[58:59]
	s_add_i32 m0, s8, 0xe000
	s_nop 0
	global_load_lds_dwordx4 v[234:235], off
	s_waitcnt vmcnt(8)
	s_waitcnt lgkmcnt(0)
	s_barrier
	s_setprio 1
	s_waitcnt lgkmcnt(0)
	v_mfma_f32_16x16x32_bf16 v[126:129], v[146:149], v[174:177], v[126:129]
	v_mfma_f32_16x16x32_bf16 v[122:125], v[154:157], v[174:177], v[122:125]
	v_mfma_f32_16x16x32_bf16 v[110:113], v[146:149], v[170:173], v[110:113]
	v_mfma_f32_16x16x32_bf16 v[106:109], v[154:157], v[170:173], v[106:109]
	v_mfma_f32_16x16x32_bf16 v[94:97], v[146:149], v[166:169], v[94:97]
	v_mfma_f32_16x16x32_bf16 v[90:93], v[154:157], v[166:169], v[90:93]
	v_mfma_f32_16x16x32_bf16 v[78:81], v[146:149], v[162:165], v[78:81]
	v_mfma_f32_16x16x32_bf16 v[74:77], v[154:157], v[162:165], v[74:77]
	v_mfma_f32_16x16x32_bf16 v[126:129], v[150:153], v[190:193], v[126:129]
	v_mfma_f32_16x16x32_bf16 v[122:125], v[158:161], v[190:193], v[122:125]
	v_mfma_f32_16x16x32_bf16 v[110:113], v[150:153], v[186:189], v[110:113]
	v_mfma_f32_16x16x32_bf16 v[106:109], v[158:161], v[186:189], v[106:109]
	v_mfma_f32_16x16x32_bf16 v[94:97], v[150:153], v[182:185], v[94:97]
	v_mfma_f32_16x16x32_bf16 v[90:93], v[158:161], v[182:185], v[90:93]
	v_mfma_f32_16x16x32_bf16 v[78:81], v[150:153], v[178:181], v[78:81]
	v_mfma_f32_16x16x32_bf16 v[74:77], v[158:161], v[178:181], v[74:77]
	s_setprio 0
	s_setprio 1
	v_mfma_f32_16x16x32_bf16 v[118:121], v[130:133], v[174:177], v[118:121]
	v_mfma_f32_16x16x32_bf16 v[114:117], v[138:141], v[174:177], v[114:117]
	v_mfma_f32_16x16x32_bf16 v[102:105], v[130:133], v[170:173], v[102:105]
	v_mfma_f32_16x16x32_bf16 v[98:101], v[138:141], v[170:173], v[98:101]
	v_mfma_f32_16x16x32_bf16 v[86:89], v[130:133], v[166:169], v[86:89]
	v_mfma_f32_16x16x32_bf16 v[82:85], v[138:141], v[166:169], v[82:85]
	v_mfma_f32_16x16x32_bf16 v[70:73], v[130:133], v[162:165], v[70:73]
	v_mfma_f32_16x16x32_bf16 v[66:69], v[138:141], v[162:165], v[66:69]
	v_mfma_f32_16x16x32_bf16 v[118:121], v[134:137], v[190:193], v[118:121]
	v_mfma_f32_16x16x32_bf16 v[114:117], v[142:145], v[190:193], v[114:117]
	v_mfma_f32_16x16x32_bf16 v[102:105], v[134:137], v[186:189], v[102:105]
	v_mfma_f32_16x16x32_bf16 v[98:101], v[142:145], v[186:189], v[98:101]
	v_mfma_f32_16x16x32_bf16 v[86:89], v[134:137], v[182:185], v[86:89]
	v_mfma_f32_16x16x32_bf16 v[82:85], v[142:145], v[182:185], v[82:85]
	v_mfma_f32_16x16x32_bf16 v[70:73], v[134:137], v[178:181], v[70:73]
	v_mfma_f32_16x16x32_bf16 v[66:69], v[142:145], v[178:181], v[66:69]
	s_setprio 0
	s_barrier
	v_cmp_ne_u32_e64 s[42:43], 1, v233
	s_andn2_b64 vcc, exec, s[44:45]
	s_cbranch_vccnz .LBB0_561
	ds_read_b128 v[174:177], v229 offset:16384
	ds_read_b128 v[190:193], v229 offset:17408
	ds_read_b128 v[170:173], v229 offset:18432
	ds_read_b128 v[186:189], v229 offset:19456
	ds_read_b128 v[166:169], v229 offset:20480
	ds_read_b128 v[182:185], v229 offset:21504
	ds_read_b128 v[162:165], v229 offset:22528
	ds_read_b128 v[178:181], v229 offset:23552

.LBB0_563:
	s_and_b64 vcc, s[40:41], s[68:69]
	v_cndmask_b32_e64 v131, v215, 0, vcc
	v_cndmask_b32_e32 v130, v214, v198, vcc
	v_lshl_add_u64 v[234:235], s[62:63], 0, v[130:131]
	s_barrier
	v_add_u32_e32 v130, 0x18000, v226
	v_add_u32_e32 v142, 0x1c000, v226
	ds_read_b128 v[146:149], v130
	ds_read_b128 v[150:153], v130 offset:1024
	ds_read_b128 v[154:157], v130 offset:2048
	ds_read_b128 v[158:161], v130 offset:3072
	ds_read_b128 v[130:133], v142
	ds_read_b128 v[134:137], v142 offset:1024
	ds_read_b128 v[138:141], v142 offset:2048
	ds_read_b128 v[142:145], v142 offset:3072
	s_mov_b32 m0, s14
	v_lshl_add_u64 v[236:237], v[234:235], 0, v[194:195]
	s_waitcnt lgkmcnt(0)
	ds_read_b128 v[174:177], v229 offset:32768
	ds_read_b128 v[190:193], v229 offset:33792
	ds_read_b128 v[170:173], v229 offset:34816
	ds_read_b128 v[186:189], v229 offset:35840
	ds_read_b128 v[166:169], v229 offset:36864
	ds_read_b128 v[182:185], v229 offset:37888
	ds_read_b128 v[162:165], v229 offset:38912
	ds_read_b128 v[178:181], v229 offset:39936
	s_mov_b32 m0, s8
	s_nop 0
	global_load_lds_dwordx4 v194, s[98:99]
	s_mov_b32 m0, s13
	s_nop 0
	global_load_lds_dwordx4 v196, s[98:99]
	s_mov_b32 m0, s14
	s_nop 0
	global_load_lds_dwordx4 v[236:237], off
	v_lshl_add_u64 v[234:235], v[234:235], 0, v[196:197]
	s_mov_b32 m0, s15
	s_nop 0
	global_load_lds_dwordx4 v[234:235], off
	s_waitcnt vmcnt(8)
	s_waitcnt lgkmcnt(0)
	s_barrier
	s_setprio 1
	s_waitcnt lgkmcnt(0)
	v_mfma_f32_16x16x32_bf16 v[126:129], v[146:149], v[174:177], v[126:129]
	v_mfma_f32_16x16x32_bf16 v[122:125], v[154:157], v[174:177], v[122:125]
	v_mfma_f32_16x16x32_bf16 v[110:113], v[146:149], v[170:173], v[110:113]
	v_mfma_f32_16x16x32_bf16 v[106:109], v[154:157], v[170:173], v[106:109]
	v_mfma_f32_16x16x32_bf16 v[94:97], v[146:149], v[166:169], v[94:97]
	v_mfma_f32_16x16x32_bf16 v[90:93], v[154:157], v[166:169], v[90:93]
	v_mfma_f32_16x16x32_bf16 v[78:81], v[146:149], v[162:165], v[78:81]
	v_mfma_f32_16x16x32_bf16 v[74:77], v[154:157], v[162:165], v[74:77]
	v_mfma_f32_16x16x32_bf16 v[126:129], v[150:153], v[190:193], v[126:129]
	v_mfma_f32_16x16x32_bf16 v[122:125], v[158:161], v[190:193], v[122:125]
	v_mfma_f32_16x16x32_bf16 v[110:113], v[150:153], v[186:189], v[110:113]
	v_mfma_f32_16x16x32_bf16 v[106:109], v[158:161], v[186:189], v[106:109]
	v_mfma_f32_16x16x32_bf16 v[94:97], v[150:153], v[182:185], v[94:97]
	v_mfma_f32_16x16x32_bf16 v[90:93], v[158:161], v[182:185], v[90:93]
	v_mfma_f32_16x16x32_bf16 v[78:81], v[150:153], v[178:181], v[78:81]
	v_mfma_f32_16x16x32_bf16 v[74:77], v[158:161], v[178:181], v[74:77]
	s_setprio 0
	s_setprio 1
	v_mfma_f32_16x16x32_bf16 v[118:121], v[130:133], v[174:177], v[118:121]
	v_mfma_f32_16x16x32_bf16 v[114:117], v[138:141], v[174:177], v[114:117]
	v_mfma_f32_16x16x32_bf16 v[102:105], v[130:133], v[170:173], v[102:105]
	v_mfma_f32_16x16x32_bf16 v[98:101], v[138:141], v[170:173], v[98:101]
	v_mfma_f32_16x16x32_bf16 v[86:89], v[130:133], v[166:169], v[86:89]
	v_mfma_f32_16x16x32_bf16 v[82:85], v[138:141], v[166:169], v[82:85]
	v_mfma_f32_16x16x32_bf16 v[70:73], v[130:133], v[162:165], v[70:73]
	v_mfma_f32_16x16x32_bf16 v[66:69], v[138:141], v[162:165], v[66:69]
	v_mfma_f32_16x16x32_bf16 v[118:121], v[134:137], v[190:193], v[118:121]
	v_mfma_f32_16x16x32_bf16 v[114:117], v[142:145], v[190:193], v[114:117]
	v_mfma_f32_16x16x32_bf16 v[102:105], v[134:137], v[186:189], v[102:105]
	v_mfma_f32_16x16x32_bf16 v[98:101], v[142:145], v[186:189], v[98:101]
	v_mfma_f32_16x16x32_bf16 v[86:89], v[134:137], v[182:185], v[86:89]
	v_mfma_f32_16x16x32_bf16 v[82:85], v[142:145], v[182:185], v[82:85]
	v_mfma_f32_16x16x32_bf16 v[70:73], v[134:137], v[178:181], v[70:73]
	v_mfma_f32_16x16x32_bf16 v[66:69], v[142:145], v[178:181], v[66:69]
	s_setprio 0
	s_barrier
	s_and_b64 vcc, exec, s[42:43]
	s_cbranch_vccnz .LBB0_565
	ds_read_b128 v[174:177], v229 offset:49152
	ds_read_b128 v[190:193], v229 offset:50176
	ds_read_b128 v[170:173], v229 offset:51200
	ds_read_b128 v[186:189], v229 offset:52224
	ds_read_b128 v[166:169], v229 offset:53248
	ds_read_b128 v[182:185], v229 offset:54272
	ds_read_b128 v[162:165], v229 offset:55296
	ds_read_b128 v[178:181], v229 offset:56320

.LBB0_761:
	ds_read_b128 v[130:133], v237
	ds_read_b128 v[134:137], v237 offset:1024
	ds_read_b128 v[138:141], v237 offset:2048
	ds_read_b128 v[142:145], v237 offset:3072
	ds_read_b128 v[146:149], v238
	ds_read_b128 v[150:153], v238 offset:1024
	ds_read_b128 v[154:157], v238 offset:2048
	ds_read_b128 v[158:161], v238 offset:3072
	s_add_u32 s48, s0, 0x21c000
	s_addc_u32 s49, s1, 0
	s_cmp_eq_u32 s67, 28
	s_cselect_b32 s42, s55, s62
	s_cselect_b32 s43, s29, s63
	s_cselect_b32 s52, s45, s48
	s_cselect_b32 s53, s31, s49
	s_add_u32 s50, s42, 0xe0000
	s_addc_u32 s51, s43, 0
	s_add_u32 s48, s52, 0x220000
	s_addc_u32 s49, s53, 0
	v_lshl_add_u64 v[208:209], s[0:1], 0, v[202:203]
	s_add_i32 m0, s9, 0xc000
	ds_read_b128 v[162:165], v239
	ds_read_b128 v[166:169], v239 offset:1024
	ds_read_b128 v[170:173], v239 offset:2048
	ds_read_b128 v[174:177], v239 offset:3072
	ds_read_b128 v[178:181], v239 offset:4096
	ds_read_b128 v[182:185], v239 offset:5120
	ds_read_b128 v[186:189], v239 offset:6144
	ds_read_b128 v[190:193], v239 offset:7168
	s_mov_b32 m0, s14
	s_nop 0
	global_load_lds_dwordx4 v194, s[100:101]
	s_mov_b32 m0, s15
	s_nop 0
	global_load_lds_dwordx4 v196, s[100:101]
	s_add_i32 m0, s9, 0xc000
	s_nop 0
	global_load_lds_dwordx4 v[208:209], off
	v_lshl_add_u64 v[208:209], s[0:1], 0, v[200:201]
	s_add_i32 m0, s9, 0xe000
	s_nop 0
	global_load_lds_dwordx4 v[208:209], off
	s_waitcnt vmcnt(8)
	s_waitcnt lgkmcnt(0)
	s_barrier
	s_setprio 1
	s_waitcnt lgkmcnt(0)
	v_mfma_f32_16x16x32_bf16 v[126:129], v[130:133], v[162:165], v[126:129]
	v_mfma_f32_16x16x32_bf16 v[122:125], v[138:141], v[162:165], v[122:125]
	v_mfma_f32_16x16x32_bf16 v[118:121], v[130:133], v[170:173], v[118:121]
	v_mfma_f32_16x16x32_bf16 v[114:117], v[138:141], v[170:173], v[114:117]
	v_mfma_f32_16x16x32_bf16 v[110:113], v[130:133], v[178:181], v[110:113]
	v_mfma_f32_16x16x32_bf16 v[106:109], v[138:141], v[178:181], v[106:109]
	v_mfma_f32_16x16x32_bf16 v[102:105], v[130:133], v[186:189], v[102:105]
	v_mfma_f32_16x16x32_bf16 v[98:101], v[138:141], v[186:189], v[98:101]
	v_mfma_f32_16x16x32_bf16 v[126:129], v[134:137], v[166:169], v[126:129]
	v_mfma_f32_16x16x32_bf16 v[122:125], v[142:145], v[166:169], v[122:125]
	v_mfma_f32_16x16x32_bf16 v[118:121], v[134:137], v[174:177], v[118:121]
	v_mfma_f32_16x16x32_bf16 v[114:117], v[142:145], v[174:177], v[114:117]
	v_mfma_f32_16x16x32_bf16 v[110:113], v[134:137], v[182:185], v[110:113]
	v_mfma_f32_16x16x32_bf16 v[106:109], v[142:145], v[182:185], v[106:109]
	v_mfma_f32_16x16x32_bf16 v[102:105], v[134:137], v[190:193], v[102:105]
	v_mfma_f32_16x16x32_bf16 v[98:101], v[142:145], v[190:193], v[98:101]
	s_setprio 0
	s_setprio 1
	v_mfma_f32_16x16x32_bf16 v[62:65], v[146:149], v[162:165], v[62:65]
	s_add_u32 s60, s52, 0x4000
	s_addc_u32 s61, s53, 0
	v_mfma_f32_16x16x32_bf16 v[58:61], v[154:157], v[162:165], v[58:61]
	v_mfma_f32_16x16x32_bf16 v[54:57], v[146:149], v[170:173], v[54:57]
	v_mfma_f32_16x16x32_bf16 v[50:53], v[154:157], v[170:173], v[50:53]
	v_mfma_f32_16x16x32_bf16 v[46:49], v[146:149], v[178:181], v[46:49]
	v_mfma_f32_16x16x32_bf16 v[42:45], v[154:157], v[178:181], v[42:45]
	v_mfma_f32_16x16x32_bf16 v[38:41], v[146:149], v[186:189], v[38:41]
	v_mfma_f32_16x16x32_bf16 v[34:37], v[154:157], v[186:189], v[34:37]
	v_mfma_f32_16x16x32_bf16 v[62:65], v[150:153], v[166:169], v[62:65]
	v_mfma_f32_16x16x32_bf16 v[58:61], v[158:161], v[166:169], v[58:61]
	v_mfma_f32_16x16x32_bf16 v[54:57], v[150:153], v[174:177], v[54:57]
	v_mfma_f32_16x16x32_bf16 v[50:53], v[158:161], v[174:177], v[50:53]
	v_mfma_f32_16x16x32_bf16 v[46:49], v[150:153], v[182:185], v[46:49]
	v_mfma_f32_16x16x32_bf16 v[42:45], v[158:161], v[182:185], v[42:45]
	v_mfma_f32_16x16x32_bf16 v[38:41], v[150:153], v[190:193], v[38:41]
	v_mfma_f32_16x16x32_bf16 v[34:37], v[158:161], v[190:193], v[34:37]
	s_setprio 0
	s_barrier
	s_add_i32 s68, s16, s8
	v_lshl_add_u64 v[208:209], s[42:43], 0, v[194:195]
	s_mov_b32 m0, s68
	ds_read_b128 v[162:165], v239 offset:16384
	ds_read_b128 v[166:169], v239 offset:17408
	ds_read_b128 v[170:173], v239 offset:18432
	ds_read_b128 v[174:177], v239 offset:19456
	ds_read_b128 v[178:181], v239 offset:20480
	ds_read_b128 v[182:185], v239 offset:21504
	ds_read_b128 v[186:189], v239 offset:22528
	ds_read_b128 v[190:193], v239 offset:23552
	global_load_lds_dwordx4 v[208:209], off
	s_add_i32 m0, s68, 0x2000
	s_add_u32 s68, s42, 0x4000
	v_lshl_add_u64 v[208:209], s[42:43], 0, v[196:197]
	s_addc_u32 s69, s43, 0
	s_add_i32 s70, s17, s8
	global_load_lds_dwordx4 v[208:209], off
	v_lshl_add_u64 v[208:209], s[68:69], 0, v[194:195]
	s_mov_b32 m0, s70
	s_nop 0
	global_load_lds_dwordx4 v[208:209], off
	v_lshl_add_u64 v[208:209], s[68:69], 0, v[196:197]
	s_add_i32 m0, s70, 0x2000
	s_nop 0
	global_load_lds_dwordx4 v[208:209], off
	s_mov_b64 s[98:99], s[52:53]
	s_waitcnt vmcnt(6)
	s_waitcnt lgkmcnt(0)
	s_barrier
	s_setprio 1
	s_waitcnt lgkmcnt(0)
	v_mfma_f32_16x16x32_bf16 v[94:97], v[130:133], v[162:165], v[94:97]
	v_mfma_f32_16x16x32_bf16 v[90:93], v[138:141], v[162:165], v[90:93]
	v_mfma_f32_16x16x32_bf16 v[86:89], v[130:133], v[170:173], v[86:89]
	v_mfma_f32_16x16x32_bf16 v[82:85], v[138:141], v[170:173], v[82:85]
	v_mfma_f32_16x16x32_bf16 v[78:81], v[130:133], v[178:181], v[78:81]
	v_mfma_f32_16x16x32_bf16 v[74:77], v[138:141], v[178:181], v[74:77]
	v_mfma_f32_16x16x32_bf16 v[70:73], v[130:133], v[186:189], v[70:73]
	v_mfma_f32_16x16x32_bf16 v[66:69], v[138:141], v[186:189], v[66:69]
	v_mfma_f32_16x16x32_bf16 v[94:97], v[134:137], v[166:169], v[94:97]
	v_mfma_f32_16x16x32_bf16 v[90:93], v[142:145], v[166:169], v[90:93]
	v_mfma_f32_16x16x32_bf16 v[86:89], v[134:137], v[174:177], v[86:89]
	v_mfma_f32_16x16x32_bf16 v[82:85], v[142:145], v[174:177], v[82:85]
	v_mfma_f32_16x16x32_bf16 v[78:81], v[134:137], v[182:185], v[78:81]
	v_mfma_f32_16x16x32_bf16 v[74:77], v[142:145], v[182:185], v[74:77]
	v_mfma_f32_16x16x32_bf16 v[70:73], v[134:137], v[190:193], v[70:73]
	v_mfma_f32_16x16x32_bf16 v[66:69], v[142:145], v[190:193], v[66:69]
	s_setprio 0
	s_setprio 1
	v_mfma_f32_16x16x32_bf16 v[30:33], v[146:149], v[162:165], v[30:33]
	v_mfma_f32_16x16x32_bf16 v[26:29], v[154:157], v[162:165], v[26:29]
	v_mfma_f32_16x16x32_bf16 v[22:25], v[146:149], v[170:173], v[22:25]
	v_mfma_f32_16x16x32_bf16 v[18:21], v[154:157], v[170:173], v[18:21]
	v_mfma_f32_16x16x32_bf16 v[14:17], v[146:149], v[178:181], v[14:17]
	v_mfma_f32_16x16x32_bf16 v[10:13], v[154:157], v[178:181], v[10:13]
	v_mfma_f32_16x16x32_bf16 v[6:9], v[146:149], v[186:189], v[6:9]
	v_mfma_f32_16x16x32_bf16 v[2:5], v[154:157], v[186:189], v[2:5]
	v_mfma_f32_16x16x32_bf16 v[30:33], v[150:153], v[166:169], v[30:33]
	v_mfma_f32_16x16x32_bf16 v[26:29], v[158:161], v[166:169], v[26:29]
	v_mfma_f32_16x16x32_bf16 v[22:25], v[150:153], v[174:177], v[22:25]
	v_mfma_f32_16x16x32_bf16 v[18:21], v[158:161], v[174:177], v[18:21]
	v_mfma_f32_16x16x32_bf16 v[14:17], v[150:153], v[182:185], v[14:17]
	v_mfma_f32_16x16x32_bf16 v[10:13], v[158:161], v[182:185], v[10:13]
	v_mfma_f32_16x16x32_bf16 v[6:9], v[150:153], v[190:193], v[6:9]
	v_mfma_f32_16x16x32_bf16 v[2:5], v[158:161], v[190:193], v[2:5]
	s_setprio 0
	s_barrier
	s_add_i32 s52, 0, 0x18000
	s_add_i32 s53, 0, 0x1c000
	v_add_u32_e32 v142, s52, v228
	v_add_u32_e32 v158, s53, v228
	ds_read_b128 v[130:133], v142
	ds_read_b128 v[134:137], v142 offset:1024
	ds_read_b128 v[138:141], v142 offset:2048
	ds_read_b128 v[142:145], v142 offset:3072
	ds_read_b128 v[146:149], v158
	ds_read_b128 v[150:153], v158 offset:1024
	ds_read_b128 v[154:157], v158 offset:2048
	ds_read_b128 v[158:161], v158 offset:3072
	s_mov_b32 m0, s11
	v_lshl_add_u64 v[208:209], s[60:61], 0, v[194:195]
	ds_read_b128 v[162:165], v239 offset:32768
	ds_read_b128 v[166:169], v239 offset:33792
	ds_read_b128 v[170:173], v239 offset:34816
	ds_read_b128 v[174:177], v239 offset:35840
	ds_read_b128 v[178:181], v239 offset:36864
	ds_read_b128 v[182:185], v239 offset:37888
	ds_read_b128 v[186:189], v239 offset:38912
	ds_read_b128 v[190:193], v239 offset:39936
	s_mov_b32 m0, s9
	s_nop 0
	global_load_lds_dwordx4 v194, s[98:99]
	s_mov_b32 m0, s10
	s_nop 0
	global_load_lds_dwordx4 v196, s[98:99]
	s_mov_b32 m0, s11
	s_nop 0
	global_load_lds_dwordx4 v[208:209], off
	v_lshl_add_u64 v[208:209], s[60:61], 0, v[196:197]
	s_mov_b32 m0, s12
	s_nop 0
	global_load_lds_dwordx4 v[208:209], off
	s_waitcnt vmcnt(8)
	s_waitcnt lgkmcnt(0)
	s_barrier
	s_setprio 1
	s_waitcnt lgkmcnt(0)
	v_mfma_f32_16x16x32_bf16 v[126:129], v[130:133], v[162:165], v[126:129]
	v_mfma_f32_16x16x32_bf16 v[122:125], v[138:141], v[162:165], v[122:125]
	v_mfma_f32_16x16x32_bf16 v[118:121], v[130:133], v[170:173], v[118:121]
	v_mfma_f32_16x16x32_bf16 v[114:117], v[138:141], v[170:173], v[114:117]
	v_mfma_f32_16x16x32_bf16 v[110:113], v[130:133], v[178:181], v[110:113]
	v_mfma_f32_16x16x32_bf16 v[106:109], v[138:141], v[178:181], v[106:109]
	v_mfma_f32_16x16x32_bf16 v[102:105], v[130:133], v[186:189], v[102:105]
	v_mfma_f32_16x16x32_bf16 v[98:101], v[138:141], v[186:189], v[98:101]
	v_mfma_f32_16x16x32_bf16 v[126:129], v[134:137], v[166:169], v[126:129]
	v_mfma_f32_16x16x32_bf16 v[122:125], v[142:145], v[166:169], v[122:125]
	v_mfma_f32_16x16x32_bf16 v[118:121], v[134:137], v[174:177], v[118:121]
	v_mfma_f32_16x16x32_bf16 v[114:117], v[142:145], v[174:177], v[114:117]
	v_mfma_f32_16x16x32_bf16 v[110:113], v[134:137], v[182:185], v[110:113]
	v_mfma_f32_16x16x32_bf16 v[106:109], v[142:145], v[182:185], v[106:109]
	v_mfma_f32_16x16x32_bf16 v[102:105], v[134:137], v[190:193], v[102:105]
	v_mfma_f32_16x16x32_bf16 v[98:101], v[142:145], v[190:193], v[98:101]
	s_setprio 0
	s_setprio 1
	v_mfma_f32_16x16x32_bf16 v[62:65], v[146:149], v[162:165], v[62:65]
	v_mfma_f32_16x16x32_bf16 v[58:61], v[154:157], v[162:165], v[58:61]
	v_mfma_f32_16x16x32_bf16 v[54:57], v[146:149], v[170:173], v[54:57]
	v_mfma_f32_16x16x32_bf16 v[50:53], v[154:157], v[170:173], v[50:53]
	v_mfma_f32_16x16x32_bf16 v[46:49], v[146:149], v[178:181], v[46:49]
	v_mfma_f32_16x16x32_bf16 v[42:45], v[154:157], v[178:181], v[42:45]
	v_mfma_f32_16x16x32_bf16 v[38:41], v[146:149], v[186:189], v[38:41]
	v_mfma_f32_16x16x32_bf16 v[34:37], v[154:157], v[186:189], v[34:37]
	v_mfma_f32_16x16x32_bf16 v[62:65], v[150:153], v[166:169], v[62:65]
	v_mfma_f32_16x16x32_bf16 v[58:61], v[158:161], v[166:169], v[58:61]
	v_mfma_f32_16x16x32_bf16 v[54:57], v[150:153], v[174:177], v[54:57]
	v_mfma_f32_16x16x32_bf16 v[50:53], v[158:161], v[174:177], v[50:53]
	v_mfma_f32_16x16x32_bf16 v[46:49], v[150:153], v[182:185], v[46:49]
	v_mfma_f32_16x16x32_bf16 v[42:45], v[158:161], v[182:185], v[42:45]
	v_mfma_f32_16x16x32_bf16 v[38:41], v[150:153], v[190:193], v[38:41]
	v_mfma_f32_16x16x32_bf16 v[34:37], v[158:161], v[190:193], v[34:37]
	s_setprio 0
	s_barrier
	s_add_i32 s52, s52, s8
	v_lshl_add_u64 v[208:209], s[50:51], 0, v[194:195]
	s_mov_b32 m0, s52
	ds_read_b128 v[162:165], v239 offset:49152
	ds_read_b128 v[166:169], v239 offset:50176
	ds_read_b128 v[170:173], v239 offset:51200
	ds_read_b128 v[174:177], v239 offset:52224
	ds_read_b128 v[178:181], v239 offset:53248
	ds_read_b128 v[182:185], v239 offset:54272
	ds_read_b128 v[186:189], v239 offset:55296
	ds_read_b128 v[190:193], v239 offset:56320
	global_load_lds_dwordx4 v[208:209], off
	s_add_i32 m0, s52, 0x2000
	s_add_u32 s42, s42, 0xe4000
	v_lshl_add_u64 v[208:209], s[50:51], 0, v[196:197]
	s_addc_u32 s43, s43, 0
	s_add_i32 s50, s53, s8
	global_load_lds_dwordx4 v[208:209], off
	v_lshl_add_u64 v[208:209], s[42:43], 0, v[194:195]
	s_mov_b32 m0, s50
	s_nop 0
	global_load_lds_dwordx4 v[208:209], off
	v_lshl_add_u64 v[208:209], s[42:43], 0, v[196:197]
	s_add_i32 m0, s50, 0x2000
	s_nop 0
	global_load_lds_dwordx4 v[208:209], off
	s_mov_b64 s[100:101], s[48:49]
	s_waitcnt vmcnt(6)
	s_waitcnt lgkmcnt(0)
	s_barrier
	s_setprio 1
	s_waitcnt lgkmcnt(0)
	v_mfma_f32_16x16x32_bf16 v[94:97], v[130:133], v[162:165], v[94:97]
	v_mfma_f32_16x16x32_bf16 v[90:93], v[138:141], v[162:165], v[90:93]
	v_mfma_f32_16x16x32_bf16 v[86:89], v[130:133], v[170:173], v[86:89]
	v_mfma_f32_16x16x32_bf16 v[82:85], v[138:141], v[170:173], v[82:85]
	v_mfma_f32_16x16x32_bf16 v[78:81], v[130:133], v[178:181], v[78:81]
	v_mfma_f32_16x16x32_bf16 v[74:77], v[138:141], v[178:181], v[74:77]
	v_mfma_f32_16x16x32_bf16 v[70:73], v[130:133], v[186:189], v[70:73]
	v_mfma_f32_16x16x32_bf16 v[66:69], v[138:141], v[186:189], v[66:69]
	v_mfma_f32_16x16x32_bf16 v[94:97], v[134:137], v[166:169], v[94:97]
	v_mfma_f32_16x16x32_bf16 v[90:93], v[142:145], v[166:169], v[90:93]
	v_mfma_f32_16x16x32_bf16 v[86:89], v[134:137], v[174:177], v[86:89]
	v_mfma_f32_16x16x32_bf16 v[82:85], v[142:145], v[174:177], v[82:85]
	v_mfma_f32_16x16x32_bf16 v[78:81], v[134:137], v[182:185], v[78:81]
	v_mfma_f32_16x16x32_bf16 v[74:77], v[142:145], v[182:185], v[74:77]
	v_mfma_f32_16x16x32_bf16 v[70:73], v[134:137], v[190:193], v[70:73]
	v_mfma_f32_16x16x32_bf16 v[66:69], v[142:145], v[190:193], v[66:69]
	s_setprio 0
	s_setprio 1
	v_mfma_f32_16x16x32_bf16 v[30:33], v[146:149], v[162:165], v[30:33]
	v_mfma_f32_16x16x32_bf16 v[26:29], v[154:157], v[162:165], v[26:29]
	v_mfma_f32_16x16x32_bf16 v[22:25], v[146:149], v[170:173], v[22:25]
	v_mfma_f32_16x16x32_bf16 v[18:21], v[154:157], v[170:173], v[18:21]
	v_mfma_f32_16x16x32_bf16 v[14:17], v[146:149], v[178:181], v[14:17]
	v_mfma_f32_16x16x32_bf16 v[10:13], v[154:157], v[178:181], v[10:13]
	v_mfma_f32_16x16x32_bf16 v[6:9], v[146:149], v[186:189], v[6:9]
	v_mfma_f32_16x16x32_bf16 v[2:5], v[154:157], v[186:189], v[2:5]
	v_mfma_f32_16x16x32_bf16 v[30:33], v[150:153], v[166:169], v[30:33]
	v_mfma_f32_16x16x32_bf16 v[26:29], v[158:161], v[166:169], v[26:29]
	v_mfma_f32_16x16x32_bf16 v[22:25], v[150:153], v[174:177], v[22:25]
	v_mfma_f32_16x16x32_bf16 v[18:21], v[158:161], v[174:177], v[18:21]
	v_mfma_f32_16x16x32_bf16 v[14:17], v[150:153], v[182:185], v[14:17]
	v_mfma_f32_16x16x32_bf16 v[10:13], v[158:161], v[182:185], v[10:13]
	v_mfma_f32_16x16x32_bf16 v[6:9], v[150:153], v[190:193], v[6:9]
	v_mfma_f32_16x16x32_bf16 v[2:5], v[158:161], v[190:193], v[2:5]
	s_setprio 0
	s_barrier
	s_add_i32 s67, s67, 2
	s_add_u32 s62, s62, 0x1c0000
	s_addc_u32 s63, s63, 0
	s_add_u32 s0, s0, 0x440000
	s_addc_u32 s1, s1, 0
	s_cmp_gt_u32 s67, 29
	s_cbranch_scc0 .LBB0_761
	s_and_b64 vcc, exec, s[26:27]
	s_cbranch_vccz .LBB0_764
	s_barrier

.LBB0_903:
	ds_read_b128 v[146:149], v225
	ds_read_b128 v[150:153], v225 offset:1024
	ds_read_b128 v[154:157], v225 offset:2048
	ds_read_b128 v[158:161], v225 offset:3072
	ds_read_b128 v[130:133], v227
	ds_read_b128 v[134:137], v227 offset:1024
	ds_read_b128 v[138:141], v227 offset:2048
	ds_read_b128 v[142:145], v227 offset:3072
	v_lshl_add_u64 v[234:235], v[210:211], 0, s[62:63]
	s_add_i32 m0, s8, 0xc000
	s_waitcnt lgkmcnt(0)
	ds_read_b128 v[174:177], v228
	ds_read_b128 v[190:193], v228 offset:1024
	ds_read_b128 v[170:173], v228 offset:2048
	ds_read_b128 v[186:189], v228 offset:3072
	ds_read_b128 v[166:169], v228 offset:4096
	ds_read_b128 v[182:185], v228 offset:5120
	ds_read_b128 v[162:165], v228 offset:6144
	ds_read_b128 v[178:181], v228 offset:7168
	s_mov_b32 m0, s23
	s_nop 0
	global_load_lds_dwordx4 v194, s[100:101]
	s_mov_b32 m0, s31
	s_nop 0
	global_load_lds_dwordx4 v196, s[100:101]
	s_add_i32 m0, s8, 0xc000
	s_nop 0
	global_load_lds_dwordx4 v[234:235], off
	v_lshl_add_u64 v[234:235], v[212:213], 0, s[62:63]
	s_add_i32 m0, s8, 0xe000
	s_nop 0
	global_load_lds_dwordx4 v[234:235], off
	s_waitcnt vmcnt(8)
	s_waitcnt lgkmcnt(0)
	s_barrier
	s_setprio 1
	s_waitcnt lgkmcnt(0)
	v_mfma_f32_16x16x32_bf16 v[126:129], v[146:149], v[174:177], v[126:129]
	v_mfma_f32_16x16x32_bf16 v[122:125], v[154:157], v[174:177], v[122:125]
	v_mfma_f32_16x16x32_bf16 v[118:121], v[146:149], v[170:173], v[118:121]
	v_mfma_f32_16x16x32_bf16 v[114:117], v[154:157], v[170:173], v[114:117]
	v_mfma_f32_16x16x32_bf16 v[110:113], v[146:149], v[166:169], v[110:113]
	v_mfma_f32_16x16x32_bf16 v[106:109], v[154:157], v[166:169], v[106:109]
	v_mfma_f32_16x16x32_bf16 v[102:105], v[146:149], v[162:165], v[102:105]
	v_mfma_f32_16x16x32_bf16 v[98:101], v[154:157], v[162:165], v[98:101]
	v_mfma_f32_16x16x32_bf16 v[126:129], v[150:153], v[190:193], v[126:129]
	v_mfma_f32_16x16x32_bf16 v[122:125], v[158:161], v[190:193], v[122:125]
	v_mfma_f32_16x16x32_bf16 v[118:121], v[150:153], v[186:189], v[118:121]
	v_mfma_f32_16x16x32_bf16 v[114:117], v[158:161], v[186:189], v[114:117]
	v_mfma_f32_16x16x32_bf16 v[110:113], v[150:153], v[182:185], v[110:113]
	v_mfma_f32_16x16x32_bf16 v[106:109], v[158:161], v[182:185], v[106:109]
	v_mfma_f32_16x16x32_bf16 v[102:105], v[150:153], v[178:181], v[102:105]
	v_mfma_f32_16x16x32_bf16 v[98:101], v[158:161], v[178:181], v[98:101]
	s_setprio 0
	s_setprio 1
	v_mfma_f32_16x16x32_bf16 v[94:97], v[130:133], v[174:177], v[94:97]
	v_mfma_f32_16x16x32_bf16 v[90:93], v[138:141], v[174:177], v[90:93]
	v_mfma_f32_16x16x32_bf16 v[86:89], v[130:133], v[170:173], v[86:89]
	v_mfma_f32_16x16x32_bf16 v[82:85], v[138:141], v[170:173], v[82:85]
	v_mfma_f32_16x16x32_bf16 v[78:81], v[130:133], v[166:169], v[78:81]
	v_mfma_f32_16x16x32_bf16 v[74:77], v[138:141], v[166:169], v[74:77]
	v_mfma_f32_16x16x32_bf16 v[70:73], v[130:133], v[162:165], v[70:73]
	v_mfma_f32_16x16x32_bf16 v[66:69], v[138:141], v[162:165], v[66:69]
	v_mfma_f32_16x16x32_bf16 v[94:97], v[134:137], v[190:193], v[94:97]
	v_mfma_f32_16x16x32_bf16 v[90:93], v[142:145], v[190:193], v[90:93]
	v_mfma_f32_16x16x32_bf16 v[86:89], v[134:137], v[186:189], v[86:89]
	v_mfma_f32_16x16x32_bf16 v[82:85], v[142:145], v[186:189], v[82:85]
	v_mfma_f32_16x16x32_bf16 v[78:81], v[134:137], v[182:185], v[78:81]
	v_mfma_f32_16x16x32_bf16 v[74:77], v[142:145], v[182:185], v[74:77]
	v_mfma_f32_16x16x32_bf16 v[70:73], v[134:137], v[178:181], v[70:73]
	v_mfma_f32_16x16x32_bf16 v[66:69], v[142:145], v[178:181], v[66:69]
	s_setprio 0
	s_barrier
	v_cmp_ne_u32_e64 s[42:43], 1, v233
	s_andn2_b64 vcc, exec, s[44:45]
	s_cbranch_vccnz .LBB0_905
	ds_read_b128 v[174:177], v228 offset:16384
	ds_read_b128 v[190:193], v228 offset:17408
	ds_read_b128 v[170:173], v228 offset:18432
	ds_read_b128 v[186:189], v228 offset:19456
	ds_read_b128 v[166:169], v228 offset:20480
	ds_read_b128 v[182:185], v228 offset:21504
	ds_read_b128 v[162:165], v228 offset:22528
	ds_read_b128 v[178:181], v228 offset:23552

.LBB0_907:
	s_and_b64 vcc, s[40:41], s[72:73]
	v_cndmask_b32_e64 v131, v209, 0, vcc
	v_cndmask_b32_e32 v130, v208, v198, vcc
	v_lshl_add_u64 v[234:235], s[70:71], 0, v[130:131]
	s_barrier
	v_add_u32_e32 v130, 0x18000, v224
	v_add_u32_e32 v142, 0x1c000, v224
	ds_read_b128 v[146:149], v130
	ds_read_b128 v[150:153], v130 offset:1024
	ds_read_b128 v[154:157], v130 offset:2048
	ds_read_b128 v[158:161], v130 offset:3072
	ds_read_b128 v[130:133], v142
	ds_read_b128 v[134:137], v142 offset:1024
	ds_read_b128 v[138:141], v142 offset:2048
	ds_read_b128 v[142:145], v142 offset:3072
	s_mov_b32 m0, s14
	v_lshl_add_u64 v[236:237], v[234:235], 0, v[194:195]
	s_waitcnt lgkmcnt(0)
	ds_read_b128 v[174:177], v228 offset:32768
	ds_read_b128 v[190:193], v228 offset:33792
	ds_read_b128 v[170:173], v228 offset:34816
	ds_read_b128 v[186:189], v228 offset:35840
	ds_read_b128 v[166:169], v228 offset:36864
	ds_read_b128 v[182:185], v228 offset:37888
	ds_read_b128 v[162:165], v228 offset:38912
	ds_read_b128 v[178:181], v228 offset:39936
	s_mov_b32 m0, s8
	s_nop 0
	global_load_lds_dwordx4 v194, s[98:99]
	s_mov_b32 m0, s13
	s_nop 0
	global_load_lds_dwordx4 v196, s[98:99]
	s_mov_b32 m0, s14
	s_nop 0
	global_load_lds_dwordx4 v[236:237], off
	v_lshl_add_u64 v[234:235], v[234:235], 0, v[196:197]
	s_mov_b32 m0, s15
	s_nop 0
	global_load_lds_dwordx4 v[234:235], off
	s_waitcnt vmcnt(8)
	s_waitcnt lgkmcnt(0)
	s_barrier
	s_setprio 1
	s_waitcnt lgkmcnt(0)
	v_mfma_f32_16x16x32_bf16 v[126:129], v[146:149], v[174:177], v[126:129]
	v_mfma_f32_16x16x32_bf16 v[122:125], v[154:157], v[174:177], v[122:125]
	v_mfma_f32_16x16x32_bf16 v[118:121], v[146:149], v[170:173], v[118:121]
	v_mfma_f32_16x16x32_bf16 v[114:117], v[154:157], v[170:173], v[114:117]
	v_mfma_f32_16x16x32_bf16 v[110:113], v[146:149], v[166:169], v[110:113]
	v_mfma_f32_16x16x32_bf16 v[106:109], v[154:157], v[166:169], v[106:109]
	v_mfma_f32_16x16x32_bf16 v[102:105], v[146:149], v[162:165], v[102:105]
	v_mfma_f32_16x16x32_bf16 v[98:101], v[154:157], v[162:165], v[98:101]
	v_mfma_f32_16x16x32_bf16 v[126:129], v[150:153], v[190:193], v[126:129]
	v_mfma_f32_16x16x32_bf16 v[122:125], v[158:161], v[190:193], v[122:125]
	v_mfma_f32_16x16x32_bf16 v[118:121], v[150:153], v[186:189], v[118:121]
	v_mfma_f32_16x16x32_bf16 v[114:117], v[158:161], v[186:189], v[114:117]
	v_mfma_f32_16x16x32_bf16 v[110:113], v[150:153], v[182:185], v[110:113]
	v_mfma_f32_16x16x32_bf16 v[106:109], v[158:161], v[182:185], v[106:109]
	v_mfma_f32_16x16x32_bf16 v[102:105], v[150:153], v[178:181], v[102:105]
	v_mfma_f32_16x16x32_bf16 v[98:101], v[158:161], v[178:181], v[98:101]
	s_setprio 0
	s_setprio 1
	v_mfma_f32_16x16x32_bf16 v[94:97], v[130:133], v[174:177], v[94:97]
	v_mfma_f32_16x16x32_bf16 v[90:93], v[138:141], v[174:177], v[90:93]
	v_mfma_f32_16x16x32_bf16 v[86:89], v[130:133], v[170:173], v[86:89]
	v_mfma_f32_16x16x32_bf16 v[82:85], v[138:141], v[170:173], v[82:85]
	v_mfma_f32_16x16x32_bf16 v[78:81], v[130:133], v[166:169], v[78:81]
	v_mfma_f32_16x16x32_bf16 v[74:77], v[138:141], v[166:169], v[74:77]
	v_mfma_f32_16x16x32_bf16 v[70:73], v[130:133], v[162:165], v[70:73]
	v_mfma_f32_16x16x32_bf16 v[66:69], v[138:141], v[162:165], v[66:69]
	v_mfma_f32_16x16x32_bf16 v[94:97], v[134:137], v[190:193], v[94:97]
	v_mfma_f32_16x16x32_bf16 v[90:93], v[142:145], v[190:193], v[90:93]
	v_mfma_f32_16x16x32_bf16 v[86:89], v[134:137], v[186:189], v[86:89]
	v_mfma_f32_16x16x32_bf16 v[82:85], v[142:145], v[186:189], v[82:85]
	v_mfma_f32_16x16x32_bf16 v[78:81], v[134:137], v[182:185], v[78:81]
	v_mfma_f32_16x16x32_bf16 v[74:77], v[142:145], v[182:185], v[74:77]
	v_mfma_f32_16x16x32_bf16 v[70:73], v[134:137], v[178:181], v[70:73]
	v_mfma_f32_16x16x32_bf16 v[66:69], v[142:145], v[178:181], v[66:69]
	s_setprio 0
	s_barrier
	s_and_b64 vcc, exec, s[42:43]
	s_cbranch_vccnz .LBB0_909
	ds_read_b128 v[174:177], v228 offset:49152
	ds_read_b128 v[190:193], v228 offset:50176
	ds_read_b128 v[170:173], v228 offset:51200
	ds_read_b128 v[186:189], v228 offset:52224
	ds_read_b128 v[166:169], v228 offset:53248
	ds_read_b128 v[182:185], v228 offset:54272
	ds_read_b128 v[162:165], v228 offset:55296
	ds_read_b128 v[178:181], v228 offset:56320

.LBB0_1289:
	v_add_u32_e32 v142, 0x14000, v229
	ds_read_b128 v[146:149], v230
	ds_read_b128 v[150:153], v230 offset:1024
	ds_read_b128 v[154:157], v230 offset:2048
	ds_read_b128 v[158:161], v230 offset:3072
	ds_read_b128 v[130:133], v142
	ds_read_b128 v[134:137], v142 offset:1024
	ds_read_b128 v[138:141], v142 offset:2048
	ds_read_b128 v[142:145], v142 offset:3072
	v_lshl_add_u64 v[234:235], v[222:223], 0, s[48:49]
	s_add_i32 m0, s8, 0xc000
	s_waitcnt lgkmcnt(0)
	ds_read_b128 v[174:177], v231
	ds_read_b128 v[190:193], v231 offset:1024
	ds_read_b128 v[170:173], v231 offset:2048
	ds_read_b128 v[186:189], v231 offset:3072
	ds_read_b128 v[166:169], v231 offset:4096
	ds_read_b128 v[182:185], v231 offset:5120
	ds_read_b128 v[162:165], v231 offset:6144
	ds_read_b128 v[178:181], v231 offset:7168
	s_mov_b32 m0, s27
	s_nop 0
	global_load_lds_dwordx4 v194, s[100:101]
	s_mov_b32 m0, s54
	s_nop 0
	global_load_lds_dwordx4 v196, s[100:101]
	s_add_i32 m0, s8, 0xc000
	s_nop 0
	global_load_lds_dwordx4 v[234:235], off
	v_lshl_add_u64 v[234:235], v[224:225], 0, s[48:49]
	s_add_i32 m0, s8, 0xe000
	s_nop 0
	global_load_lds_dwordx4 v[234:235], off
	s_waitcnt vmcnt(8)
	s_waitcnt lgkmcnt(0)
	s_barrier
	s_setprio 1
	s_waitcnt lgkmcnt(0)
	v_mfma_f32_16x16x32_bf16 v[126:129], v[146:149], v[174:177], v[126:129]
	v_mfma_f32_16x16x32_bf16 v[122:125], v[154:157], v[174:177], v[122:125]
	v_mfma_f32_16x16x32_bf16 v[118:121], v[146:149], v[170:173], v[118:121]
	v_mfma_f32_16x16x32_bf16 v[110:113], v[154:157], v[170:173], v[110:113]
	v_mfma_f32_16x16x32_bf16 v[102:105], v[146:149], v[166:169], v[102:105]
	v_mfma_f32_16x16x32_bf16 v[94:97], v[154:157], v[166:169], v[94:97]
	v_mfma_f32_16x16x32_bf16 v[86:89], v[146:149], v[162:165], v[86:89]
	v_mfma_f32_16x16x32_bf16 v[78:81], v[154:157], v[162:165], v[78:81]
	v_mfma_f32_16x16x32_bf16 v[126:129], v[150:153], v[190:193], v[126:129]
	v_mfma_f32_16x16x32_bf16 v[122:125], v[158:161], v[190:193], v[122:125]
	v_mfma_f32_16x16x32_bf16 v[118:121], v[150:153], v[186:189], v[118:121]
	v_mfma_f32_16x16x32_bf16 v[110:113], v[158:161], v[186:189], v[110:113]
	v_mfma_f32_16x16x32_bf16 v[102:105], v[150:153], v[182:185], v[102:105]
	v_mfma_f32_16x16x32_bf16 v[94:97], v[158:161], v[182:185], v[94:97]
	v_mfma_f32_16x16x32_bf16 v[86:89], v[150:153], v[178:181], v[86:89]
	v_mfma_f32_16x16x32_bf16 v[78:81], v[158:161], v[178:181], v[78:81]
	s_setprio 0
	s_setprio 1
	v_mfma_f32_16x16x32_bf16 v[114:117], v[130:133], v[174:177], v[114:117]
	v_mfma_f32_16x16x32_bf16 v[106:109], v[138:141], v[174:177], v[106:109]
	v_mfma_f32_16x16x32_bf16 v[98:101], v[130:133], v[170:173], v[98:101]
	v_mfma_f32_16x16x32_bf16 v[90:93], v[138:141], v[170:173], v[90:93]
	v_mfma_f32_16x16x32_bf16 v[82:85], v[130:133], v[166:169], v[82:85]
	v_mfma_f32_16x16x32_bf16 v[74:77], v[138:141], v[166:169], v[74:77]
	v_mfma_f32_16x16x32_bf16 v[70:73], v[130:133], v[162:165], v[70:73]
	v_mfma_f32_16x16x32_bf16 v[66:69], v[138:141], v[162:165], v[66:69]
	v_mfma_f32_16x16x32_bf16 v[114:117], v[134:137], v[190:193], v[114:117]
	v_mfma_f32_16x16x32_bf16 v[106:109], v[142:145], v[190:193], v[106:109]
	v_mfma_f32_16x16x32_bf16 v[98:101], v[134:137], v[186:189], v[98:101]
	v_mfma_f32_16x16x32_bf16 v[90:93], v[142:145], v[186:189], v[90:93]
	v_mfma_f32_16x16x32_bf16 v[82:85], v[134:137], v[182:185], v[82:85]
	v_mfma_f32_16x16x32_bf16 v[74:77], v[142:145], v[182:185], v[74:77]
	v_mfma_f32_16x16x32_bf16 v[70:73], v[134:137], v[178:181], v[70:73]
	v_mfma_f32_16x16x32_bf16 v[66:69], v[142:145], v[178:181], v[66:69]
	s_setprio 0
	s_barrier
	v_cndmask_b32_e64 v233, 0, 1, s[40:41]
	v_cmp_ne_u32_e64 s[42:43], 1, v233
	s_andn2_b64 vcc, exec, s[40:41]
	s_cbranch_vccnz .LBB0_1291
	ds_read_b128 v[174:177], v231 offset:16384
	ds_read_b128 v[190:193], v231 offset:17408
	ds_read_b128 v[170:173], v231 offset:18432
	ds_read_b128 v[186:189], v231 offset:19456
	ds_read_b128 v[166:169], v231 offset:20480
	ds_read_b128 v[182:185], v231 offset:21504
	ds_read_b128 v[162:165], v231 offset:22528
	ds_read_b128 v[178:181], v231 offset:23552

.LBB0_1293:
	s_and_b64 vcc, s[34:35], s[58:59]
	v_cndmask_b32_e64 v131, v221, 0, vcc
	v_cndmask_b32_e32 v130, v220, v198, vcc
	v_lshl_add_u64 v[234:235], s[56:57], 0, v[130:131]
	s_barrier
	v_add_u32_e32 v130, 0x18000, v229
	v_add_u32_e32 v142, 0x1c000, v229
	ds_read_b128 v[146:149], v130
	ds_read_b128 v[150:153], v130 offset:1024
	ds_read_b128 v[154:157], v130 offset:2048
	ds_read_b128 v[158:161], v130 offset:3072
	ds_read_b128 v[130:133], v142
	ds_read_b128 v[134:137], v142 offset:1024
	ds_read_b128 v[138:141], v142 offset:2048
	ds_read_b128 v[142:145], v142 offset:3072
	s_mov_b32 m0, s14
	v_lshl_add_u64 v[236:237], v[234:235], 0, v[194:195]
	s_waitcnt lgkmcnt(0)
	ds_read_b128 v[174:177], v231 offset:32768
	ds_read_b128 v[190:193], v231 offset:33792
	ds_read_b128 v[170:173], v231 offset:34816
	ds_read_b128 v[186:189], v231 offset:35840
	ds_read_b128 v[166:169], v231 offset:36864
	ds_read_b128 v[182:185], v231 offset:37888
	ds_read_b128 v[162:165], v231 offset:38912
	ds_read_b128 v[178:181], v231 offset:39936
	s_mov_b32 m0, s8
	s_nop 0
	global_load_lds_dwordx4 v194, s[98:99]
	s_mov_b32 m0, s13
	s_nop 0
	global_load_lds_dwordx4 v196, s[98:99]
	s_mov_b32 m0, s14
	s_nop 0
	global_load_lds_dwordx4 v[236:237], off
	v_lshl_add_u64 v[234:235], v[234:235], 0, v[196:197]
	s_mov_b32 m0, s15
	s_nop 0
	global_load_lds_dwordx4 v[234:235], off
	s_waitcnt vmcnt(8)
	s_waitcnt lgkmcnt(0)
	s_barrier
	s_setprio 1
	s_waitcnt lgkmcnt(0)
	v_mfma_f32_16x16x32_bf16 v[126:129], v[146:149], v[174:177], v[126:129]
	v_mfma_f32_16x16x32_bf16 v[122:125], v[154:157], v[174:177], v[122:125]
	v_mfma_f32_16x16x32_bf16 v[118:121], v[146:149], v[170:173], v[118:121]
	v_mfma_f32_16x16x32_bf16 v[110:113], v[154:157], v[170:173], v[110:113]
	v_mfma_f32_16x16x32_bf16 v[102:105], v[146:149], v[166:169], v[102:105]
	v_mfma_f32_16x16x32_bf16 v[94:97], v[154:157], v[166:169], v[94:97]
	v_mfma_f32_16x16x32_bf16 v[86:89], v[146:149], v[162:165], v[86:89]
	v_mfma_f32_16x16x32_bf16 v[78:81], v[154:157], v[162:165], v[78:81]
	v_mfma_f32_16x16x32_bf16 v[126:129], v[150:153], v[190:193], v[126:129]
	v_mfma_f32_16x16x32_bf16 v[122:125], v[158:161], v[190:193], v[122:125]
	v_mfma_f32_16x16x32_bf16 v[118:121], v[150:153], v[186:189], v[118:121]
	v_mfma_f32_16x16x32_bf16 v[110:113], v[158:161], v[186:189], v[110:113]
	v_mfma_f32_16x16x32_bf16 v[102:105], v[150:153], v[182:185], v[102:105]
	v_mfma_f32_16x16x32_bf16 v[94:97], v[158:161], v[182:185], v[94:97]
	v_mfma_f32_16x16x32_bf16 v[86:89], v[150:153], v[178:181], v[86:89]
	v_mfma_f32_16x16x32_bf16 v[78:81], v[158:161], v[178:181], v[78:81]
	s_setprio 0
	s_setprio 1
	v_mfma_f32_16x16x32_bf16 v[114:117], v[130:133], v[174:177], v[114:117]
	v_mfma_f32_16x16x32_bf16 v[106:109], v[138:141], v[174:177], v[106:109]
	v_mfma_f32_16x16x32_bf16 v[98:101], v[130:133], v[170:173], v[98:101]
	v_mfma_f32_16x16x32_bf16 v[90:93], v[138:141], v[170:173], v[90:93]
	v_mfma_f32_16x16x32_bf16 v[82:85], v[130:133], v[166:169], v[82:85]
	v_mfma_f32_16x16x32_bf16 v[74:77], v[138:141], v[166:169], v[74:77]
	v_mfma_f32_16x16x32_bf16 v[70:73], v[130:133], v[162:165], v[70:73]
	v_mfma_f32_16x16x32_bf16 v[66:69], v[138:141], v[162:165], v[66:69]
	v_mfma_f32_16x16x32_bf16 v[114:117], v[134:137], v[190:193], v[114:117]
	v_mfma_f32_16x16x32_bf16 v[106:109], v[142:145], v[190:193], v[106:109]
	v_mfma_f32_16x16x32_bf16 v[98:101], v[134:137], v[186:189], v[98:101]
	v_mfma_f32_16x16x32_bf16 v[90:93], v[142:145], v[186:189], v[90:93]
	v_mfma_f32_16x16x32_bf16 v[82:85], v[134:137], v[182:185], v[82:85]
	v_mfma_f32_16x16x32_bf16 v[74:77], v[142:145], v[182:185], v[74:77]
	v_mfma_f32_16x16x32_bf16 v[70:73], v[134:137], v[178:181], v[70:73]
	v_mfma_f32_16x16x32_bf16 v[66:69], v[142:145], v[178:181], v[66:69]
	s_setprio 0
	s_barrier
	s_and_b64 vcc, exec, s[42:43]
	s_cbranch_vccnz .LBB0_1295
	ds_read_b128 v[174:177], v231 offset:49152
	ds_read_b128 v[190:193], v231 offset:50176
	ds_read_b128 v[170:173], v231 offset:51200
	ds_read_b128 v[186:189], v231 offset:52224
	ds_read_b128 v[166:169], v231 offset:53248
	ds_read_b128 v[182:185], v231 offset:54272
	ds_read_b128 v[162:165], v231 offset:55296
	ds_read_b128 v[178:181], v231 offset:56320

.LBB0_1612:
	v_add_u32_e32 v1, 0x10000, v232
	ds_read_b128 v[146:149], v1
	ds_read_b128 v[150:153], v1 offset:1024
	ds_read_b128 v[154:157], v1 offset:2048
	ds_read_b128 v[158:161], v1 offset:3072
	v_add_u32_e32 v1, 0x14000, v232
	ds_read_b128 v[130:133], v1
	ds_read_b128 v[134:137], v1 offset:1024
	ds_read_b128 v[138:141], v1 offset:2048
	ds_read_b128 v[142:145], v1 offset:3072
	v_lshl_add_u64 v[236:237], v[226:227], 0, s[48:49]
	s_add_i32 m0, s9, 0xc000
	s_waitcnt lgkmcnt(0)
	ds_read_b128 v[174:177], v233
	ds_read_b128 v[190:193], v233 offset:1024
	ds_read_b128 v[170:173], v233 offset:2048
	ds_read_b128 v[186:189], v233 offset:3072
	ds_read_b128 v[166:169], v233 offset:4096
	ds_read_b128 v[182:185], v233 offset:5120
	ds_read_b128 v[162:165], v233 offset:6144
	ds_read_b128 v[178:181], v233 offset:7168
	s_mov_b32 m0, s54
	s_nop 0
	global_load_lds_dwordx4 v194, s[100:101]
	s_mov_b32 m0, s55
	s_nop 0
	global_load_lds_dwordx4 v196, s[100:101]
	s_add_i32 m0, s9, 0xc000
	s_nop 0
	global_load_lds_dwordx4 v[236:237], off
	v_lshl_add_u64 v[236:237], v[228:229], 0, s[48:49]
	s_add_i32 m0, s9, 0xe000
	s_nop 0
	global_load_lds_dwordx4 v[236:237], off
	s_waitcnt vmcnt(8)
	s_waitcnt lgkmcnt(0)
	s_barrier
	s_setprio 1
	s_waitcnt lgkmcnt(0)
	v_mfma_f32_16x16x32_bf16 v[126:129], v[146:149], v[174:177], v[126:129]
	v_mfma_f32_16x16x32_bf16 v[122:125], v[154:157], v[174:177], v[122:125]
	v_mfma_f32_16x16x32_bf16 v[118:121], v[146:149], v[170:173], v[118:121]
	v_mfma_f32_16x16x32_bf16 v[110:113], v[154:157], v[170:173], v[110:113]
	v_mfma_f32_16x16x32_bf16 v[102:105], v[146:149], v[166:169], v[102:105]
	v_mfma_f32_16x16x32_bf16 v[94:97], v[154:157], v[166:169], v[94:97]
	v_mfma_f32_16x16x32_bf16 v[86:89], v[146:149], v[162:165], v[86:89]
	v_mfma_f32_16x16x32_bf16 v[78:81], v[154:157], v[162:165], v[78:81]
	v_mfma_f32_16x16x32_bf16 v[126:129], v[150:153], v[190:193], v[126:129]
	v_mfma_f32_16x16x32_bf16 v[122:125], v[158:161], v[190:193], v[122:125]
	v_mfma_f32_16x16x32_bf16 v[118:121], v[150:153], v[186:189], v[118:121]
	v_mfma_f32_16x16x32_bf16 v[110:113], v[158:161], v[186:189], v[110:113]
	v_mfma_f32_16x16x32_bf16 v[102:105], v[150:153], v[182:185], v[102:105]
	v_mfma_f32_16x16x32_bf16 v[94:97], v[158:161], v[182:185], v[94:97]
	v_mfma_f32_16x16x32_bf16 v[86:89], v[150:153], v[178:181], v[86:89]
	v_mfma_f32_16x16x32_bf16 v[78:81], v[158:161], v[178:181], v[78:81]
	s_setprio 0
	s_setprio 1
	v_mfma_f32_16x16x32_bf16 v[114:117], v[130:133], v[174:177], v[114:117]
	v_mfma_f32_16x16x32_bf16 v[106:109], v[138:141], v[174:177], v[106:109]
	v_mfma_f32_16x16x32_bf16 v[98:101], v[130:133], v[170:173], v[98:101]
	v_mfma_f32_16x16x32_bf16 v[90:93], v[138:141], v[170:173], v[90:93]
	v_mfma_f32_16x16x32_bf16 v[82:85], v[130:133], v[166:169], v[82:85]
	v_mfma_f32_16x16x32_bf16 v[74:77], v[138:141], v[166:169], v[74:77]
	v_mfma_f32_16x16x32_bf16 v[70:73], v[130:133], v[162:165], v[70:73]
	v_mfma_f32_16x16x32_bf16 v[66:69], v[138:141], v[162:165], v[66:69]
	v_mfma_f32_16x16x32_bf16 v[114:117], v[134:137], v[190:193], v[114:117]
	v_mfma_f32_16x16x32_bf16 v[106:109], v[142:145], v[190:193], v[106:109]
	v_mfma_f32_16x16x32_bf16 v[98:101], v[134:137], v[186:189], v[98:101]
	v_mfma_f32_16x16x32_bf16 v[90:93], v[142:145], v[186:189], v[90:93]
	v_mfma_f32_16x16x32_bf16 v[82:85], v[134:137], v[182:185], v[82:85]
	v_mfma_f32_16x16x32_bf16 v[74:77], v[142:145], v[182:185], v[74:77]
	v_mfma_f32_16x16x32_bf16 v[70:73], v[134:137], v[178:181], v[70:73]
	v_mfma_f32_16x16x32_bf16 v[66:69], v[142:145], v[178:181], v[66:69]
	s_setprio 0
	s_barrier
	v_cndmask_b32_e64 v1, 0, 1, s[40:41]
	v_cmp_ne_u32_e64 s[42:43], 1, v1
	s_andn2_b64 vcc, exec, s[40:41]
	s_cbranch_vccnz .LBB0_1614
	ds_read_b128 v[174:177], v233 offset:16384
	ds_read_b128 v[190:193], v233 offset:17408
	ds_read_b128 v[170:173], v233 offset:18432
	ds_read_b128 v[186:189], v233 offset:19456
	ds_read_b128 v[166:169], v233 offset:20480
	ds_read_b128 v[182:185], v233 offset:21504
	ds_read_b128 v[162:165], v233 offset:22528
	ds_read_b128 v[178:181], v233 offset:23552

.LBB0_1616:
	s_and_b64 vcc, s[38:39], s[56:57]
	v_cndmask_b32_e64 v131, v225, 0, vcc
	v_cndmask_b32_e32 v130, v224, v198, vcc
	v_lshl_add_u64 v[236:237], s[52:53], 0, v[130:131]
	s_barrier
	v_add_u32_e32 v1, 0x18000, v232
	ds_read_b128 v[146:149], v1
	ds_read_b128 v[150:153], v1 offset:1024
	ds_read_b128 v[154:157], v1 offset:2048
	ds_read_b128 v[158:161], v1 offset:3072
	v_add_u32_e32 v1, 0x1c000, v232
	ds_read_b128 v[130:133], v1
	ds_read_b128 v[134:137], v1 offset:1024
	ds_read_b128 v[138:141], v1 offset:2048
	ds_read_b128 v[142:145], v1 offset:3072
	s_mov_b32 m0, s15
	v_lshl_add_u64 v[238:239], v[236:237], 0, v[194:195]
	s_waitcnt lgkmcnt(0)
	ds_read_b128 v[174:177], v233 offset:32768
	ds_read_b128 v[190:193], v233 offset:33792
	ds_read_b128 v[170:173], v233 offset:34816
	ds_read_b128 v[186:189], v233 offset:35840
	ds_read_b128 v[166:169], v233 offset:36864
	ds_read_b128 v[182:185], v233 offset:37888
	ds_read_b128 v[162:165], v233 offset:38912
	ds_read_b128 v[178:181], v233 offset:39936
	s_mov_b32 m0, s9
	s_nop 0
	global_load_lds_dwordx4 v194, s[98:99]
	s_mov_b32 m0, s14
	s_nop 0
	global_load_lds_dwordx4 v196, s[98:99]
	s_mov_b32 m0, s15
	s_nop 0
	global_load_lds_dwordx4 v[238:239], off
	v_lshl_add_u64 v[236:237], v[236:237], 0, v[196:197]
	s_mov_b32 m0, s16
	s_nop 0
	global_load_lds_dwordx4 v[236:237], off
	s_waitcnt vmcnt(8)
	s_waitcnt lgkmcnt(0)
	s_barrier
	s_setprio 1
	s_waitcnt lgkmcnt(0)
	v_mfma_f32_16x16x32_bf16 v[126:129], v[146:149], v[174:177], v[126:129]
	v_mfma_f32_16x16x32_bf16 v[122:125], v[154:157], v[174:177], v[122:125]
	v_mfma_f32_16x16x32_bf16 v[118:121], v[146:149], v[170:173], v[118:121]
	v_mfma_f32_16x16x32_bf16 v[110:113], v[154:157], v[170:173], v[110:113]
	v_mfma_f32_16x16x32_bf16 v[102:105], v[146:149], v[166:169], v[102:105]
	v_mfma_f32_16x16x32_bf16 v[94:97], v[154:157], v[166:169], v[94:97]
	v_mfma_f32_16x16x32_bf16 v[86:89], v[146:149], v[162:165], v[86:89]
	v_mfma_f32_16x16x32_bf16 v[78:81], v[154:157], v[162:165], v[78:81]
	v_mfma_f32_16x16x32_bf16 v[126:129], v[150:153], v[190:193], v[126:129]
	v_mfma_f32_16x16x32_bf16 v[122:125], v[158:161], v[190:193], v[122:125]
	v_mfma_f32_16x16x32_bf16 v[118:121], v[150:153], v[186:189], v[118:121]
	v_mfma_f32_16x16x32_bf16 v[110:113], v[158:161], v[186:189], v[110:113]
	v_mfma_f32_16x16x32_bf16 v[102:105], v[150:153], v[182:185], v[102:105]
	v_mfma_f32_16x16x32_bf16 v[94:97], v[158:161], v[182:185], v[94:97]
	v_mfma_f32_16x16x32_bf16 v[86:89], v[150:153], v[178:181], v[86:89]
	v_mfma_f32_16x16x32_bf16 v[78:81], v[158:161], v[178:181], v[78:81]
	s_setprio 0
	s_setprio 1
	v_mfma_f32_16x16x32_bf16 v[114:117], v[130:133], v[174:177], v[114:117]
	v_mfma_f32_16x16x32_bf16 v[106:109], v[138:141], v[174:177], v[106:109]
	v_mfma_f32_16x16x32_bf16 v[98:101], v[130:133], v[170:173], v[98:101]
	v_mfma_f32_16x16x32_bf16 v[90:93], v[138:141], v[170:173], v[90:93]
	v_mfma_f32_16x16x32_bf16 v[82:85], v[130:133], v[166:169], v[82:85]
	v_mfma_f32_16x16x32_bf16 v[74:77], v[138:141], v[166:169], v[74:77]
	v_mfma_f32_16x16x32_bf16 v[70:73], v[130:133], v[162:165], v[70:73]
	v_mfma_f32_16x16x32_bf16 v[66:69], v[138:141], v[162:165], v[66:69]
	v_mfma_f32_16x16x32_bf16 v[114:117], v[134:137], v[190:193], v[114:117]
	v_mfma_f32_16x16x32_bf16 v[106:109], v[142:145], v[190:193], v[106:109]
	v_mfma_f32_16x16x32_bf16 v[98:101], v[134:137], v[186:189], v[98:101]
	v_mfma_f32_16x16x32_bf16 v[90:93], v[142:145], v[186:189], v[90:93]
	v_mfma_f32_16x16x32_bf16 v[82:85], v[134:137], v[182:185], v[82:85]
	v_mfma_f32_16x16x32_bf16 v[74:77], v[142:145], v[182:185], v[74:77]
	v_mfma_f32_16x16x32_bf16 v[70:73], v[134:137], v[178:181], v[70:73]
	v_mfma_f32_16x16x32_bf16 v[66:69], v[142:145], v[178:181], v[66:69]
	s_setprio 0
	s_barrier
	s_and_b64 vcc, exec, s[42:43]
	s_cbranch_vccnz .LBB0_1618
	ds_read_b128 v[174:177], v233 offset:49152
	ds_read_b128 v[190:193], v233 offset:50176
	ds_read_b128 v[170:173], v233 offset:51200
	ds_read_b128 v[186:189], v233 offset:52224
	ds_read_b128 v[166:169], v233 offset:53248
	ds_read_b128 v[182:185], v233 offset:54272
	ds_read_b128 v[162:165], v233 offset:55296
	ds_read_b128 v[178:181], v233 offset:56320
